# NA units rebalanced 4/12 between scan and non-scan blocks; scan state published with 16-byte stores via v_permlane16_swap
# speedup vs baseline: 1.0802x; 1.0084x over previous
.LBB0_320:
	s_and_b64 vcc, exec, s[0:1]
	s_cbranch_vccz .LBB0_463
	s_waitcnt vmcnt(0) lgkmcnt(0)
	v_bfe_u32 v0, v133, 4, 2
	s_mov_b64 s[0:1], -1
	s_cmpk_gt_i32 s2, 0x7f
	v_and_b32_e32 v129, 15, v163
	v_lshrrev_b32_e32 v135, 4, v133
	v_lshlrev_b32_e32 v158, 3, v133
	v_lshrrev_b32_e32 v101, 2, v163
	v_lshlrev_b32_e32 v128, 2, v0
	v_lshrrev_b32_e32 v154, 3, v133
	v_lshlrev_b32_e32 v157, 3, v0
	v_lshl_add_u32 v155, v0, 4, v161
	v_lshlrev_b32_e32 v156, 2, v133
	s_cbranch_scc0 .LBB0_379
	v_and_b32_e32 v0, 48, v101
	v_or_b32_e32 v107, v0, v129
	v_sub_u32_e64 v0, v0, 8 clamp
	v_min_u32_e32 v126, 32, v0
	v_add_u32_e32 v53, v126, v128
	v_sub_u32_e32 v0, v53, v107
	v_sub_u32_e64 v1, v107, 8 clamp
	v_max_i32_e32 v0, -15, v0
	v_min_u32_e32 v52, 48, v1
	v_add_u32_e32 v0, 15, v0
	v_add_u32_e32 v54, 16, v52
	v_min_u32_e32 v55, 30, v0
	v_or_b32_e32 v0, 1, v53
	v_cmp_lt_u32_e64 s[6:7], v0, v52
	v_cmp_ge_u32_e64 s[8:9], v0, v54
	v_sub_u32_e32 v0, v0, v107
	v_max_i32_e32 v0, -15, v0
	v_add_u32_e32 v0, 15, v0
	v_min_u32_e32 v56, 30, v0
	v_or_b32_e32 v0, 2, v53
	v_cmp_lt_u32_e64 s[10:11], v0, v52
	v_cmp_ge_u32_e64 s[12:13], v0, v54
	v_sub_u32_e32 v0, v0, v107
	v_max_i32_e32 v0, -15, v0
	v_add_u32_e32 v0, 15, v0
	v_min_u32_e32 v57, 30, v0
	v_or_b32_e32 v0, 3, v53
	v_cmp_lt_u32_e64 s[14:15], v0, v52
	v_cmp_ge_u32_e64 s[16:17], v0, v54
	v_sub_u32_e32 v0, v0, v107
	v_max_i32_e32 v0, -15, v0
	s_mul_i32 s0, s2, 24
	v_add_u32_e32 v0, 15, v0
	s_addk_i32 s0, 0xf400
	v_min_u32_e32 v58, 30, v0
	v_add_u32_e32 v0, 16, v53
	v_add_u32_e32 v103, s0, v162
	v_cmp_lt_u32_e64 s[18:19], v0, v52
	v_sub_u32_e32 v0, v0, v107
	v_max_i32_e32 v0, -15, v0
	v_and_b32_e32 v44, 63, v103
	v_add_u32_e32 v59, 15, v0
	v_sub_u32_e64 v0, v44, 4 clamp
	s_add_i32 s3, 0, 0x240a8
	v_min_u32_e32 v7, 56, v0
	v_mov_b32_e32 v0, s3
	ds_read_b64 v[2:3], v0
	v_lshlrev_b32_e32 v0, 3, v103
	s_movk_i32 s72, 0xf000
	v_and_or_b32 v45, v0, s72, v154
	v_lshl_or_b32 v0, v7, 6, v45
	v_ashrrev_i32_e32 v1, 31, v0
	v_and_b32_e32 v6, 0x1c0, v103
	v_lshlrev_b64 v[0:1], 10, v[0:1]
	v_and_b32_e32 v100, 56, v158
	s_waitcnt lgkmcnt(0)
	v_lshl_add_u64 v[4:5], v[2:3], 0, v[0:1]
	v_lshlrev_b32_e32 v0, 1, v6
	v_mov_b32_e32 v1, 0
	v_lshl_add_u64 v[4:5], v[4:5], 0, v[0:1]
	v_lshlrev_b32_e32 v36, 1, v100
	v_mov_b32_e32 v37, v1
	v_lshl_add_u64 v[12:13], v[4:5], 0, v[36:37]
	s_mov_b32 s74, 0x8800000
	v_add_co_u32_e32 v14, vcc, s74, v12
	s_movk_i32 s73, 0xffc0
	s_nop 0
	v_addc_co_u32_e32 v15, vcc, 0, v13, vcc
	s_mov_b32 s75, 0x8808000
	v_and_or_b32 v4, v103, s73, v135
	v_add_co_u32_e32 v16, vcc, s75, v12
	v_ashrrev_i32_e32 v5, 31, v4
	s_nop 0
	v_addc_co_u32_e32 v17, vcc, 0, v13, vcc
	s_mov_b32 s76, 0x8810000
	v_lshlrev_b64 v[4:5], 13, v[4:5]
	v_add_co_u32_e32 v20, vcc, s76, v12
	v_and_b32_e32 v102, 0x78, v158
	v_lshl_add_u64 v[4:5], v[2:3], 0, v[4:5]
	v_lshlrev_b32_e32 v6, 7, v7
	v_mov_b32_e32 v7, v1
	v_addc_co_u32_e32 v21, vcc, 0, v13, vcc
	s_mov_b32 s77, 0x8818000
	v_lshl_add_u64 v[4:5], v[4:5], 0, v[6:7]
	v_lshlrev_b32_e32 v38, 1, v102
	v_mov_b32_e32 v39, v1
	v_add_co_u32_e32 v22, vcc, s77, v12
	v_lshl_add_u64 v[28:29], v[4:5], 0, v[38:39]
	s_nop 0
	v_addc_co_u32_e32 v23, vcc, 0, v13, vcc
	s_mov_b32 s78, 0xa800000
	v_add_co_u32_e32 v30, vcc, s78, v28
	s_mov_b32 s79, 0xa820000
	s_nop 0
	v_addc_co_u32_e32 v31, vcc, 0, v29, vcc
	v_add_co_u32_e32 v32, vcc, s79, v28
	s_mov_b32 s80, 0xa840000
	s_nop 0
	v_addc_co_u32_e32 v33, vcc, 0, v29, vcc
	v_add_co_u32_e32 v40, vcc, s80, v28
	s_mov_b32 s81, 0xa860000
	s_nop 0
	v_addc_co_u32_e32 v41, vcc, 0, v29, vcc
	v_add_co_u32_e32 v42, vcc, s81, v28
	flat_load_dwordx4 v[4:7], v[14:15]
	flat_load_dwordx4 v[8:11], v[16:17]
	s_nop 0
	flat_load_dwordx4 v[12:15], v[20:21]
	flat_load_dwordx4 v[16:19], v[22:23]
	s_nop 0
	flat_load_dwordx4 v[20:23], v[30:31]
	flat_load_dwordx4 v[24:27], v[32:33]
	v_addc_co_u32_e32 v43, vcc, 0, v29, vcc
	flat_load_dwordx4 v[28:31], v[40:41]
	flat_load_dwordx4 v[32:35], v[42:43]
	v_lshl_or_b32 v40, v44, 6, v45
	v_ashrrev_i32_e32 v41, 31, v40
	v_lshlrev_b64 v[40:41], 10, v[40:41]
	v_lshl_add_u64 v[2:3], v[2:3], 0, v[40:41]
	v_lshl_add_u64 v[2:3], v[2:3], 0, v[0:1]
	v_lshl_add_u64 v[2:3], v[2:3], 0, v[36:37]
	s_mov_b32 s82, 0x6800000
	v_add_co_u32_e32 v40, vcc, s82, v2
	s_mov_b32 s20, 0x6808000
	s_nop 0
	v_addc_co_u32_e32 v41, vcc, 0, v3, vcc
	v_add_co_u32_e32 v2, vcc, s20, v2
	v_mul_u32_u24_e32 v39, 0x48, v154
	s_nop 0
	v_addc_co_u32_e32 v3, vcc, 0, v3, vcc
	flat_load_dwordx4 v[44:47], v[40:41]
	flat_load_dwordx4 v[48:51], v[2:3]
	v_lshlrev_b32_e32 v39, 1, v39
	v_add3_u32 v127, v161, v39, v36
	v_mul_u32_u24_e32 v36, 0x110, v135
	v_add3_u32 v130, v161, v36, v38
	v_mbcnt_lo_u32_b32 v38, -1, 0
	v_mbcnt_hi_u32_b32 v38, -1, v38
	v_and_b32_e32 v40, 64, v38
	v_xor_b32_e32 v39, 16, v38
	v_add_u32_e32 v40, 64, v40
	v_cmp_lt_i32_e32 vcc, v39, v40
	v_add_u32_e32 v2, 17, v53
	v_add_u32_e32 v3, 18, v53
	v_add_u32_e32 v37, 19, v53
	v_cndmask_b32_e32 v39, v38, v39, vcc
	v_cmp_lt_u32_e64 s[20:21], v2, v52
	v_cmp_ge_u32_e64 s[22:23], v2, v54
	v_sub_u32_e32 v2, v2, v107
	v_cmp_lt_u32_e64 s[24:25], v3, v52
	v_cmp_ge_u32_e64 s[26:27], v3, v54
	v_sub_u32_e32 v3, v3, v107
	v_cmp_lt_u32_e64 s[28:29], v37, v52
	v_cmp_ge_u32_e64 s[30:31], v37, v54
	v_sub_u32_e32 v37, v37, v107
	v_lshlrev_b32_e32 v134, 2, v39
	v_xor_b32_e32 v39, 32, v38
	v_max_i32_e32 v2, -15, v2
	v_max_i32_e32 v3, -15, v3
	v_max_i32_e32 v37, -15, v37
	v_cmp_lt_i32_e32 vcc, v39, v40
	v_min_u32_e32 v0, 30, v59
	v_add_u32_e32 v2, 15, v2
	v_add_u32_e32 v3, 15, v3
	v_add_u32_e32 v37, 15, v37
	v_cndmask_b32_e32 v38, v38, v39, vcc
	v_min_u32_e32 v2, 30, v2
	v_min_u32_e32 v3, 30, v3
	v_min_u32_e32 v37, 30, v37
	v_sub_u32_e32 v36, v155, v157
	s_movk_i32 s83, 0x90
	v_lshlrev_b32_e32 v136, 2, v38
	v_mul_u32_u24_e32 v38, 0x88, v129
	v_lshl_add_u32 v144, v0, 2, v161
	v_add3_u32 v0, v160, v156, 0
	v_cmp_ge_u32_e64 s[0:1], v53, v52
	v_cmp_lt_u32_e64 s[36:37], v53, v52
	v_cmp_ge_u32_e64 s[4:5], v53, v54
	s_mov_b32 s39, 0
	v_mad_u32_u24 v131, v107, s83, v155
	v_or_b32_e32 v137, 64, v126
	v_mul_u32_u24_e32 v138, 0x90, v129
	v_lshl_add_u32 v139, v38, 1, v36
	v_lshl_add_u32 v140, v55, 2, v161
	v_lshl_add_u32 v141, v56, 2, v161
	v_lshl_add_u32 v142, v57, 2, v161
	v_lshl_add_u32 v143, v58, 2, v161
	v_lshl_add_u32 v145, v2, 2, v161
	v_lshl_add_u32 v146, v3, 2, v161
	v_lshl_add_u32 v148, v37, 2, v161
	v_add_u32_e32 v149, 0xb000, v0
	v_or_b32_e32 v150, 0xffffff00, v133
	s_add_i32 s84, 0, 0x24040
	s_mov_b64 s[42:43], 0x400
	s_movk_i32 s85, 0xd0
	s_mov_b64 s[44:45], 0x1c800000
	s_mov_b64 s[46:47], 0x1ca00000
	s_mov_b64 s[48:49], 0x8800000
	s_mov_b64 s[50:51], 0xa800000
	s_mov_b32 s86, 0x8000
	s_mov_b32 s87, 0x10000
	s_mov_b32 s88, 0xf149f2ca
	s_mov_b32 s89, 0xefa18f08
	v_lshlrev_b32_e32 v104, 1, v128
	s_mov_b64 s[52:53], 0x6800000
	v_mov_b32_e32 v151, 0xf149f2ca
	s_mov_b32 s90, 0
	s_branch .LBB0_324
.LBB0_323:
	ds_bpermute_b32 v0, v134, v164
	v_lshlrev_b32_e32 v69, 3, v152
	v_lshlrev_b32_e32 v70, 6, v105
	v_and_b32_e32 v69, 0xfffff000, v69
	v_mov_b32_e32 v2, s3
	s_waitcnt lgkmcnt(0)
	v_add_f32_e32 v0, v164, v0
	ds_bpermute_b32 v68, v136, v0
	ds_read_b64 v[2:3], v2
	v_mov_b32_e32 v105, v1
	s_add_i32 s90, s90, 1
	s_cmp_eq_u32 s90, 12
	s_waitcnt lgkmcnt(1)
	v_add_f32_e32 v0, v0, v68
	v_div_scale_f32 v71, s[34:35], v0, v0, 1.0
	v_rcp_f32_e32 v72, v71
	v_or3_b32 v68, v69, v70, v107
	v_div_scale_f32 v69, vcc, 1.0, v0, 1.0
	v_fma_f32 v70, -v71, v72, 1.0
	v_fmac_f32_e32 v72, v70, v72
	v_mul_f32_e32 v70, v69, v72
	v_fma_f32 v73, -v71, v70, v69
	v_fmac_f32_e32 v70, v73, v72
	v_fma_f32 v69, -v71, v70, v69
	v_div_fmas_f32 v69, v69, v72, v70
	v_div_fixup_f32 v70, v69, v0, 1.0
	v_ashrrev_i32_e32 v69, 31, v68
	v_lshlrev_b64 v[68:69], 10, v[68:69]
	s_waitcnt lgkmcnt(0)
	v_lshl_add_u64 v[2:3], v[2:3], 0, v[68:69]
	v_lshlrev_b32_e32 v0, 1, v106
	v_lshl_add_u64 v[2:3], v[2:3], 0, v[0:1]
	v_lshl_add_u64 v[2:3], v[2:3], 0, v[104:105]
	v_lshl_add_u64 v[68:69], v[2:3], 0, s[52:53]
	v_pk_mul_f32 v[64:65], v[64:65], v[70:71] op_sel_hi:[1,0]
	v_pk_mul_f32 v[66:67], v[66:67], v[70:71] op_sel_hi:[1,0]
	v_add_co_u32_e32 v2, vcc, s82, v2
	v_cvt_pk_bf16_f32 v64, v64, v65
	v_cvt_pk_bf16_f32 v65, v66, v67
	v_addc_co_u32_e32 v3, vcc, 0, v3, vcc
	global_store_dwordx2 v[2:3], v[64:65], off
	v_pk_mul_f32 v[2:3], v[60:61], v[70:71] op_sel_hi:[1,0]
	v_pk_mul_f32 v[60:61], v[62:63], v[70:71] op_sel_hi:[1,0]
	v_cvt_pk_bf16_f32 v2, v2, v3
	v_cvt_pk_bf16_f32 v3, v60, v61
	global_store_dwordx2 v[68:69], v[2:3], off offset:32
	v_pk_mul_f32 v[2:3], v[56:57], v[70:71] op_sel_hi:[1,0]
	v_pk_mul_f32 v[56:57], v[58:59], v[70:71] op_sel_hi:[1,0]
	v_cvt_pk_bf16_f32 v2, v2, v3
	v_cvt_pk_bf16_f32 v3, v56, v57
	global_store_dwordx2 v[68:69], v[2:3], off offset:64
	v_pk_mul_f32 v[2:3], v[52:53], v[70:71] op_sel_hi:[1,0]
	v_pk_mul_f32 v[52:53], v[54:55], v[70:71] op_sel_hi:[1,0]
	v_cvt_pk_bf16_f32 v2, v2, v3
	v_cvt_pk_bf16_f32 v3, v52, v53
	global_store_dwordx2 v[68:69], v[2:3], off offset:96
	s_cbranch_scc1 .LBB0_378
.LBB0_324:
	v_lshl_add_u32 v152, s90, 1, v103
	v_bfe_u32 v2, v152, 6, 3
	v_mul_u32_u24_e32 v53, 0x1d1, v2
	v_lshlrev_b32_e32 v106, 6, v2
	v_and_b32_e32 v2, 0xfffffe00, v152
	v_or3_b32 v2, v2, v135, v106
	v_add_u32_e32 v55, 2, v152
	v_ashrrev_i32_e32 v3, 31, v2
	v_and_b32_e32 v57, 63, v55
	v_lshlrev_b64 v[108:109], 9, v[2:3]
	v_lshlrev_b64 v[110:111], 13, v[2:3]
	v_sub_u32_e64 v2, v57, 4 clamp
	v_min_u32_e32 v2, 56, v2
	v_lshlrev_b32_e32 v3, 3, v55
	v_lshlrev_b32_e32 v56, 6, v2
	v_and_or_b32 v58, v3, s72, v154
	v_or_b32_e32 v2, v58, v56
	v_ashrrev_i32_e32 v3, 31, v2
	v_and_b32_e32 v105, 63, v152
	v_lshlrev_b64 v[112:113], 10, v[2:3]
	v_and_or_b32 v2, v55, s73, v135
	v_sub_u32_e64 v0, v105, 4 clamp
	v_ashrrev_i32_e32 v3, 31, v2
	v_min_u32_e32 v0, 56, v0
	v_ashrrev_i32_e32 v52, 9, v152
	v_lshlrev_b64 v[114:115], 13, v[2:3]
	v_lshl_or_b32 v2, v57, 6, v58
	v_lshl_or_b32 v153, v52, 8, v154
	v_lshlrev_b32_e32 v54, 12, v52
	v_lshlrev_b32_e32 v52, 6, v0
	v_ashrrev_i32_e32 v3, 31, v2
	v_or3_b32 v159, v54, v154, v52
	v_and_b32_e32 v54, 0x1c0, v55
	v_lshlrev_b64 v[116:117], 10, v[2:3]
	v_sub_u32_e32 v0, v0, v105
	v_mov_b32_e32 v2, v1
	v_mov_b32_e32 v3, v1
	s_cmp_lt_u32 s90, 11
	v_add_u32_e32 v163, 7, v0
	v_add_lshl_u32 v118, v133, v53, 2
	v_mov_b32_e32 v0, v1
	v_lshlrev_b32_e32 v120, 1, v52
	v_lshlrev_b32_e32 v122, 1, v54
	v_lshlrev_b32_e32 v124, 1, v56
	v_mov_b64_e32 v[54:55], v[2:3]
	v_mov_b64_e32 v[58:59], v[2:3]
	v_mov_b64_e32 v[62:63], v[2:3]
	v_mov_b64_e32 v[66:67], v[2:3]
	s_cselect_b64 s[54:55], -1, 0
	v_mov_b32_e32 v119, v1
	v_mov_b64_e32 v[52:53], v[0:1]
	v_mov_b64_e32 v[56:57], v[0:1]
	v_mov_b64_e32 v[60:61], v[0:1]
	v_mov_b64_e32 v[64:65], v[0:1]
	v_mov_b32_e32 v164, v1
	v_mov_b32_e32 v165, 0xf149f2ca
	s_mov_b32 s91, s39
	s_branch .LBB0_326

.LBB0_389:
	v_cndmask_b32_e64 v130, 0, 1, s[8:9]
	v_cmp_ne_u32_e64 s[4:5], 1, v130
	s_andn2_b64 vcc, exec, s[8:9]
	v_lshlrev_b32_e32 v130, 1, v128
	s_cbranch_vccnz .LBB0_391
	v_mov_b32_e32 v131, s14
	ds_read_b64 v[168:169], v131
	v_lshlrev_b64 v[170:171], 17, v[136:137]
	v_mov_b32_e32 v153, v137
	v_mov_b32_e32 v131, v137
	s_waitcnt lgkmcnt(0)
	v_lshl_add_u64 v[168:169], v[168:169], 0, v[170:171]
	v_lshl_add_u64 v[168:169], v[168:169], 0, v[148:149]
	v_lshl_add_u64 v[168:169], v[168:169], 0, v[150:151]
	v_lshl_add_u64 v[168:169], v[168:169], 0, v[152:153]
	v_and_b32_e32 v170, 4, v128
	v_lshlrev_b32_e32 v170, 3, v170
	v_and_b32_e32 v171, 8, v128
	v_lshl_add_u32 v170, v171, 1, v170
	v_mov_b32_e32 v171, 0
	v_lshl_add_u64 v[168:169], v[168:169], 0, v[170:171]
	v_cvt_pk_bf16_f32 v240, v124, v125
	v_cvt_pk_bf16_f32 v241, v126, v127
	v_cvt_pk_bf16_f32 v242, v120, v121
	v_cvt_pk_bf16_f32 v243, v122, v123
	s_nop 1
	v_permlane16_swap_b32_e32 v240, v242
	v_permlane16_swap_b32_e32 v241, v243
	global_store_dwordx4 v[168:169], v[240:243], off
	v_cvt_pk_bf16_f32 v244, v112, v113
	v_cvt_pk_bf16_f32 v245, v114, v115
	v_cvt_pk_bf16_f32 v246, v108, v109
	v_cvt_pk_bf16_f32 v247, v110, v111
	s_nop 1
	v_permlane16_swap_b32_e32 v244, v246
	v_permlane16_swap_b32_e32 v245, v247
	global_store_dwordx4 v[168:169], v[244:247], off offset:64
	v_cvt_pk_bf16_f32 v248, v104, v105
	v_cvt_pk_bf16_f32 v249, v106, v107
	v_cvt_pk_bf16_f32 v250, v100, v101
	v_cvt_pk_bf16_f32 v251, v102, v103
	s_nop 1
	v_permlane16_swap_b32_e32 v248, v250
	v_permlane16_swap_b32_e32 v249, v251
	global_store_dwordx4 v[168:169], v[248:251], off offset:128
	v_cvt_pk_bf16_f32 v252, v96, v97
	v_cvt_pk_bf16_f32 v253, v98, v99
	v_cvt_pk_bf16_f32 v254, v116, v117
	v_cvt_pk_bf16_f32 v255, v118, v119
	s_nop 1
	v_permlane16_swap_b32_e32 v252, v254
	v_permlane16_swap_b32_e32 v253, v255
	global_store_dwordx4 v[168:169], v[252:255], off offset:192

.LBB0_393:
	s_waitcnt lgkmcnt(0)
	s_barrier
	ds_read_b128 v[168:171], v167
	ds_read_b128 v[172:175], v166 offset:34816
	ds_read_b128 v[176:179], v167 offset:4352
	v_pk_mul_f32 v[126:127], v[142:143], v[126:127]
	v_pk_mul_f32 v[124:125], v[140:141], v[124:125]
	ds_read_b128 v[180:183], v167 offset:8704
	ds_read_b128 v[184:187], v166 offset:34880
	ds_read_b128 v[188:191], v167 offset:64
	v_pk_mul_f32 v[122:123], v[142:143], v[122:123]
	s_waitcnt lgkmcnt(0)
	v_mfma_f32_16x16x32_bf16 v[124:127], v[168:171], v[172:175], v[124:127]
	ds_read_b128 v[168:171], v167 offset:13056
	ds_read_b128 v[192:195], v167 offset:4416
	v_pk_mul_f32 v[120:121], v[140:141], v[120:121]
	v_pk_mul_f32 v[114:115], v[142:143], v[114:115]
	v_pk_mul_f32 v[112:113], v[140:141], v[112:113]
	v_pk_mul_f32 v[110:111], v[142:143], v[110:111]
	v_pk_mul_f32 v[108:109], v[140:141], v[108:109]
	v_mfma_f32_16x16x32_bf16 v[120:123], v[176:179], v[172:175], v[120:123]
	ds_read_b128 v[176:179], v167 offset:17408
	ds_read_b128 v[196:199], v167 offset:8768
	v_pk_mul_f32 v[106:107], v[142:143], v[106:107]
	v_pk_mul_f32 v[104:105], v[140:141], v[104:105]
	v_mfma_f32_16x16x32_bf16 v[112:115], v[180:183], v[172:175], v[112:115]
	ds_read_b128 v[180:183], v167 offset:21760
	ds_read_b128 v[200:203], v167 offset:13120
	v_pk_mul_f32 v[102:103], v[142:143], v[102:103]
	v_pk_mul_f32 v[100:101], v[140:141], v[100:101]
	s_waitcnt lgkmcnt(0)
	v_mfma_f32_16x16x32_bf16 v[108:111], v[168:171], v[172:175], v[108:111]
	ds_read_b128 v[168:171], v167 offset:26112
	ds_read_b128 v[204:207], v167 offset:17472
	v_pk_mul_f32 v[98:99], v[142:143], v[98:99]
	v_pk_mul_f32 v[96:97], v[140:141], v[96:97]
	v_mfma_f32_16x16x32_bf16 v[104:107], v[176:179], v[172:175], v[104:107]
	ds_read_b128 v[176:179], v167 offset:30464
	ds_read_b128 v[208:211], v167 offset:21824
	v_pk_mul_f32 v[118:119], v[142:143], v[118:119]
	v_pk_mul_f32 v[116:117], v[140:141], v[116:117]
	v_mfma_f32_16x16x32_bf16 v[100:103], v[180:183], v[172:175], v[100:103]
	ds_read_b128 v[180:183], v167 offset:26176
	s_and_b64 vcc, exec, s[8:9]
	s_waitcnt lgkmcnt(0)
	v_mfma_f32_16x16x32_bf16 v[96:99], v[168:171], v[172:175], v[96:99]
	ds_read_b128 v[168:171], v167 offset:30528
	v_mfma_f32_16x16x32_bf16 v[116:119], v[176:179], v[172:175], v[116:119]
	ds_read_b128 v[172:175], v167 offset:128
	v_mfma_f32_16x16x32_bf16 v[124:127], v[188:191], v[184:187], v[124:127]
	v_mfma_f32_16x16x32_bf16 v[96:99], v[180:183], v[184:187], v[96:99]
	s_waitcnt lgkmcnt(0)
	v_mfma_f32_16x16x32_bf16 v[116:119], v[168:171], v[184:187], v[116:119]
	ds_read_b128 v[168:171], v166 offset:34944
	ds_read_b128 v[176:179], v166 offset:35008
	ds_read_b128 v[180:183], v167 offset:192
	v_mfma_f32_16x16x32_bf16 v[120:123], v[192:195], v[184:187], v[120:123]
	v_mfma_f32_16x16x32_bf16 v[112:115], v[196:199], v[184:187], v[112:115]
	v_mfma_f32_16x16x32_bf16 v[108:111], v[200:203], v[184:187], v[108:111]
	v_mfma_f32_16x16x32_bf16 v[104:107], v[204:207], v[184:187], v[104:107]
	v_mfma_f32_16x16x32_bf16 v[100:103], v[208:211], v[184:187], v[100:103]
	s_waitcnt lgkmcnt(0)
	v_mfma_f32_16x16x32_bf16 v[124:127], v[172:175], v[168:171], v[124:127]
	ds_read_b128 v[172:175], v167 offset:4480
	ds_read_b128 v[184:187], v167 offset:4544
	s_waitcnt lgkmcnt(0)
	v_mfma_f32_16x16x32_bf16 v[120:123], v[172:175], v[168:171], v[120:123]
	ds_read_b128 v[172:175], v167 offset:8832
	ds_read_b128 v[188:191], v167 offset:8896
	s_waitcnt lgkmcnt(0)
	v_mfma_f32_16x16x32_bf16 v[112:115], v[172:175], v[168:171], v[112:115]
	ds_read_b128 v[172:175], v167 offset:13184
	ds_read_b128 v[192:195], v167 offset:13248
	s_waitcnt lgkmcnt(0)
	v_mfma_f32_16x16x32_bf16 v[108:111], v[172:175], v[168:171], v[108:111]
	ds_read_b128 v[172:175], v167 offset:17536
	ds_read_b128 v[196:199], v167 offset:17600
	s_waitcnt lgkmcnt(0)
	v_mfma_f32_16x16x32_bf16 v[104:107], v[172:175], v[168:171], v[104:107]
	ds_read_b128 v[172:175], v167 offset:21888
	ds_read_b128 v[200:203], v167 offset:21952
	s_waitcnt lgkmcnt(0)
	v_mfma_f32_16x16x32_bf16 v[100:103], v[172:175], v[168:171], v[100:103]
	ds_read_b128 v[172:175], v167 offset:26240
	ds_read_b128 v[204:207], v167 offset:26304
	s_waitcnt lgkmcnt(0)
	v_mfma_f32_16x16x32_bf16 v[96:99], v[172:175], v[168:171], v[96:99]
	ds_read_b128 v[172:175], v167 offset:30592
	ds_read_b128 v[208:211], v167 offset:30656
	s_waitcnt lgkmcnt(0)
	s_barrier
	s_waitcnt vmcnt(4)
	v_mfma_f32_16x16x32_bf16 v[168:171], v[172:175], v[168:171], v[116:119]
	v_mfma_f32_16x16x32_bf16 v[124:127], v[180:183], v[176:179], v[124:127]
	v_mfma_f32_16x16x32_bf16 v[120:123], v[184:187], v[176:179], v[120:123]
	v_mfma_f32_16x16x32_bf16 v[116:119], v[188:191], v[176:179], v[112:115]
	v_mfma_f32_16x16x32_bf16 v[112:115], v[192:195], v[176:179], v[108:111]
	v_mfma_f32_16x16x32_bf16 v[108:111], v[196:199], v[176:179], v[104:107]
	v_mfma_f32_16x16x32_bf16 v[104:107], v[200:203], v[176:179], v[100:103]
	v_mfma_f32_16x16x32_bf16 v[100:103], v[204:207], v[176:179], v[96:99]
	v_mfma_f32_16x16x32_bf16 v[96:99], v[208:211], v[176:179], v[168:171]
	s_cbranch_vccz .LBB0_405
	s_and_saveexec_b64 s[8:9], s[6:7]
	s_xor_b64 s[8:9], exec, s[8:9]
	s_or_b32 s24, s24, 1
	s_sub_i32 s25, 33, s24
	s_or_saveexec_b64 s[8:9], s[8:9]
	v_mov_b32_e32 v136, s25
	s_xor_b64 exec, exec, s[8:9]
	s_add_i32 s24, s3, -1
	v_mov_b32_e32 v136, s24
	s_or_b64 exec, exec, s[8:9]
	s_add_i32 s8, s3, 1
	s_cbranch_execnz .LBB0_400

.LBB0_400:
	s_and_b64 vcc, exec, s[4:5]
	s_cbranch_vccnz .LBB0_402
	v_mov_b32_e32 v131, s14
	ds_read_b64 v[168:169], v131
	v_lshlrev_b64 v[170:171], 17, v[136:137]
	v_mov_b32_e32 v153, v137
	v_mov_b32_e32 v131, v137
	s_waitcnt lgkmcnt(0)
	v_lshl_add_u64 v[168:169], v[168:169], 0, v[170:171]
	v_lshl_add_u64 v[168:169], v[168:169], 0, v[148:149]
	v_lshl_add_u64 v[168:169], v[168:169], 0, v[150:151]
	v_lshl_add_u64 v[168:169], v[168:169], 0, v[152:153]
	v_and_b32_e32 v170, 4, v128
	v_lshlrev_b32_e32 v170, 3, v170
	v_and_b32_e32 v171, 8, v128
	v_lshl_add_u32 v170, v171, 1, v170
	v_mov_b32_e32 v171, 0
	v_lshl_add_u64 v[168:169], v[168:169], 0, v[170:171]
	v_cvt_pk_bf16_f32 v240, v124, v125
	v_cvt_pk_bf16_f32 v241, v126, v127
	v_cvt_pk_bf16_f32 v242, v120, v121
	v_cvt_pk_bf16_f32 v243, v122, v123
	s_nop 1
	v_permlane16_swap_b32_e32 v240, v242
	v_permlane16_swap_b32_e32 v241, v243
	global_store_dwordx4 v[168:169], v[240:243], off
	v_cvt_pk_bf16_f32 v244, v116, v117
	v_cvt_pk_bf16_f32 v245, v118, v119
	v_cvt_pk_bf16_f32 v246, v112, v113
	v_cvt_pk_bf16_f32 v247, v114, v115
	s_nop 1
	v_permlane16_swap_b32_e32 v244, v246
	v_permlane16_swap_b32_e32 v245, v247
	global_store_dwordx4 v[168:169], v[244:247], off offset:64
	v_cvt_pk_bf16_f32 v248, v108, v109
	v_cvt_pk_bf16_f32 v249, v110, v111
	v_cvt_pk_bf16_f32 v250, v104, v105
	v_cvt_pk_bf16_f32 v251, v106, v107
	s_nop 1
	v_permlane16_swap_b32_e32 v248, v250
	v_permlane16_swap_b32_e32 v249, v251
	global_store_dwordx4 v[168:169], v[248:251], off offset:128
	v_cvt_pk_bf16_f32 v252, v100, v101
	v_cvt_pk_bf16_f32 v253, v102, v103
	v_cvt_pk_bf16_f32 v254, v96, v97
	v_cvt_pk_bf16_f32 v255, v98, v99
	s_nop 1
	v_permlane16_swap_b32_e32 v252, v254
	v_permlane16_swap_b32_e32 v253, v255
	global_store_dwordx4 v[168:169], v[252:255], off offset:192

.LBB0_406:
	s_waitcnt vmcnt(0)
	v_sub_u32_e64 v0, v163, 8 clamp
	v_min_u32_e32 v42, 48, v0
	v_sub_u32_e64 v0, v165, 8 clamp
	v_min_u32_e32 v105, 32, v0
	v_add_u32_e32 v43, v105, v128
	v_sub_u32_e32 v0, v43, v163
	v_max_i32_e32 v0, -15, v0
	v_add_u32_e32 v0, 15, v0
	v_add_u32_e32 v52, 16, v42
	v_min_u32_e32 v53, 30, v0
	v_or_b32_e32 v0, 1, v43
	v_cmp_lt_u32_e64 s[6:7], v0, v42
	v_cmp_ge_u32_e64 s[8:9], v0, v52
	v_sub_u32_e32 v0, v0, v163
	v_max_i32_e32 v0, -15, v0
	v_add_u32_e32 v0, 15, v0
	v_min_u32_e32 v54, 30, v0
	v_or_b32_e32 v0, 2, v43
	v_cmp_lt_u32_e64 s[10:11], v0, v42
	v_cmp_ge_u32_e64 s[12:13], v0, v52
	v_sub_u32_e32 v0, v0, v163
	v_max_i32_e32 v0, -15, v0
	v_add_u32_e32 v0, 15, v0
	v_min_u32_e32 v55, 30, v0
	v_or_b32_e32 v0, 3, v43
	s_mul_i32 s0, s2, 8
	v_cmp_lt_u32_e64 s[14:15], v0, v42
	v_cmp_ge_u32_e64 s[16:17], v0, v52
	v_sub_u32_e32 v0, v0, v163
	s_addk_i32 s0, 0xc00
	v_max_i32_e32 v0, -15, v0
	v_add_u32_e32 v101, s0, v162
	v_add_u32_e32 v0, 15, v0
	v_min_u32_e32 v56, 30, v0
	v_add_u32_e32 v0, 16, v43
	v_and_b32_e32 v44, 63, v101
	v_cmp_lt_u32_e64 s[18:19], v0, v42
	v_sub_u32_e32 v57, v0, v163
	v_sub_u32_e64 v0, v44, 4 clamp
	s_add_i32 s3, 0, 0x240a8
	v_min_u32_e32 v7, 56, v0
	v_mov_b32_e32 v0, s3
	ds_read_b64 v[2:3], v0
	v_lshlrev_b32_e32 v0, 3, v101
	s_movk_i32 s72, 0xf000
	v_and_or_b32 v45, v0, s72, v154
	v_lshl_or_b32 v0, v7, 6, v45
	v_ashrrev_i32_e32 v1, 31, v0
	v_and_b32_e32 v6, 0x1c0, v101
	v_lshlrev_b64 v[0:1], 10, v[0:1]
	v_and_b32_e32 v100, 56, v158
	s_waitcnt lgkmcnt(0)
	v_lshl_add_u64 v[4:5], v[2:3], 0, v[0:1]
	v_lshlrev_b32_e32 v0, 1, v6
	v_mov_b32_e32 v1, 0
	v_lshl_add_u64 v[4:5], v[4:5], 0, v[0:1]
	v_lshlrev_b32_e32 v36, 1, v100
	v_mov_b32_e32 v37, v1
	v_lshl_add_u64 v[12:13], v[4:5], 0, v[36:37]
	s_mov_b32 s20, 0x8800000
	v_add_co_u32_e32 v14, vcc, s20, v12
	s_movk_i32 s73, 0xffc0
	s_nop 0
	v_addc_co_u32_e32 v15, vcc, 0, v13, vcc
	s_mov_b32 s20, 0x8808000
	v_and_or_b32 v4, v101, s73, v135
	v_add_co_u32_e32 v16, vcc, s20, v12
	v_ashrrev_i32_e32 v5, 31, v4
	s_nop 0
	v_addc_co_u32_e32 v17, vcc, 0, v13, vcc
	s_mov_b32 s20, 0x8810000
	v_lshlrev_b64 v[4:5], 13, v[4:5]
	v_add_co_u32_e32 v20, vcc, s20, v12
	v_lshl_add_u64 v[4:5], v[2:3], 0, v[4:5]
	v_lshlrev_b32_e32 v6, 7, v7
	v_mov_b32_e32 v7, v1
	v_addc_co_u32_e32 v21, vcc, 0, v13, vcc
	s_mov_b32 s20, 0x8818000
	v_lshl_add_u64 v[4:5], v[4:5], 0, v[6:7]
	v_lshlrev_b32_e32 v102, 1, v134
	v_mov_b32_e32 v103, v1
	v_add_co_u32_e32 v22, vcc, s20, v12
	v_lshl_add_u64 v[28:29], v[4:5], 0, v[102:103]
	s_nop 0
	v_addc_co_u32_e32 v23, vcc, 0, v13, vcc
	s_mov_b32 s20, 0xa800000
	v_add_co_u32_e32 v30, vcc, s20, v28
	s_mov_b32 s20, 0xa820000
	s_nop 0
	v_addc_co_u32_e32 v31, vcc, 0, v29, vcc
	v_add_co_u32_e32 v32, vcc, s20, v28
	s_mov_b32 s20, 0xa840000
	s_nop 0
	v_addc_co_u32_e32 v33, vcc, 0, v29, vcc
	v_add_co_u32_e32 v38, vcc, s20, v28
	s_mov_b32 s20, 0xa860000
	s_nop 0
	v_addc_co_u32_e32 v39, vcc, 0, v29, vcc
	v_add_co_u32_e32 v40, vcc, s20, v28
	flat_load_dwordx4 v[4:7], v[14:15]
	flat_load_dwordx4 v[8:11], v[16:17]
	s_nop 0
	flat_load_dwordx4 v[12:15], v[20:21]
	flat_load_dwordx4 v[16:19], v[22:23]
	s_nop 0
	flat_load_dwordx4 v[20:23], v[30:31]
	flat_load_dwordx4 v[24:27], v[32:33]
	v_addc_co_u32_e32 v41, vcc, 0, v29, vcc
	flat_load_dwordx4 v[28:31], v[38:39]
	flat_load_dwordx4 v[32:35], v[40:41]
	v_lshl_or_b32 v38, v44, 6, v45
	v_ashrrev_i32_e32 v39, 31, v38
	v_lshlrev_b64 v[38:39], 10, v[38:39]
	v_lshl_add_u64 v[2:3], v[2:3], 0, v[38:39]
	v_lshl_add_u64 v[2:3], v[2:3], 0, v[0:1]
	v_lshl_add_u64 v[2:3], v[2:3], 0, v[36:37]
	s_mov_b32 s74, 0x6800000
	v_add_co_u32_e32 v38, vcc, s74, v2
	s_mov_b32 s20, 0x6808000
	s_nop 0
	v_addc_co_u32_e32 v39, vcc, 0, v3, vcc
	v_add_co_u32_e32 v2, vcc, s20, v2
	v_add_u32_e32 v37, 19, v43
	s_nop 0
	v_addc_co_u32_e32 v3, vcc, 0, v3, vcc
	flat_load_dwordx4 v[44:47], v[38:39]
	flat_load_dwordx4 v[48:51], v[2:3]
	v_mul_u32_u24_e32 v38, 0x48, v154
	v_lshlrev_b32_e32 v38, 1, v38
	v_add3_u32 v124, v161, v38, v36
	v_mul_u32_u24_e32 v38, 0x90, v163
	v_lshlrev_b32_e32 v39, 1, v157
	v_add3_u32 v125, v161, v38, v39
	v_mbcnt_lo_u32_b32 v38, -1, 0
	v_mbcnt_hi_u32_b32 v38, -1, v38
	v_and_b32_e32 v40, 64, v38
	v_xor_b32_e32 v39, 16, v38
	v_add_u32_e32 v40, 64, v40
	v_add_u32_e32 v2, 17, v43
	v_add_u32_e32 v3, 18, v43
	v_cmp_lt_i32_e32 vcc, v39, v40
	v_max_i32_e32 v0, -15, v57
	v_cmp_lt_u32_e64 s[20:21], v2, v42
	v_cmp_ge_u32_e64 s[22:23], v2, v52
	v_sub_u32_e32 v2, v2, v163
	v_cmp_lt_u32_e64 s[24:25], v3, v42
	v_cmp_ge_u32_e64 s[26:27], v3, v52
	v_sub_u32_e32 v3, v3, v163
	v_cmp_lt_u32_e64 s[28:29], v37, v42
	v_cmp_ge_u32_e64 s[30:31], v37, v52
	v_sub_u32_e32 v37, v37, v163
	v_cndmask_b32_e32 v39, v38, v39, vcc
	v_add_u32_e32 v0, 15, v0
	v_max_i32_e32 v2, -15, v2
	v_max_i32_e32 v3, -15, v3
	v_max_i32_e32 v37, -15, v37
	v_lshlrev_b32_e32 v126, 2, v39
	v_xor_b32_e32 v39, 32, v38
	v_min_u32_e32 v0, 30, v0
	v_add_u32_e32 v2, 15, v2
	v_add_u32_e32 v3, 15, v3
	v_add_u32_e32 v37, 15, v37
	v_cmp_lt_i32_e32 vcc, v39, v40
	v_min_u32_e32 v2, 30, v2
	v_min_u32_e32 v3, 30, v3
	v_min_u32_e32 v37, 30, v37
	v_sub_u32_e32 v36, v155, v157
	v_cndmask_b32_e32 v38, v38, v39, vcc
	v_lshl_add_u32 v141, v0, 2, v161
	v_add3_u32 v0, v160, v156, 0
	v_cmp_ge_u32_e64 s[0:1], v43, v42
	v_cmp_lt_u32_e64 s[36:37], v43, v42
	v_cmp_ge_u32_e64 s[4:5], v43, v52
	s_mov_b32 s39, 0
	s_movk_i32 s75, 0x90
	v_lshlrev_b32_e32 v127, 2, v38
	v_or_b32_e32 v128, 64, v105
	v_mul_u32_u24_e32 v134, 0x90, v129
	v_lshl_add_u32 v136, v164, 1, v36
	v_lshl_add_u32 v137, v53, 2, v161
	v_lshl_add_u32 v138, v54, 2, v161
	v_lshl_add_u32 v139, v55, 2, v161
	v_lshl_add_u32 v140, v56, 2, v161
	v_lshl_add_u32 v142, v2, 2, v161
	v_lshl_add_u32 v143, v3, 2, v161
	v_lshl_add_u32 v144, v37, 2, v161
	v_add_u32_e32 v145, 0xb000, v0
	v_or_b32_e32 v146, 0xffffff00, v133
	s_add_i32 s76, 0, 0x24040
	s_mov_b64 s[42:43], 0x400
	s_movk_i32 s77, 0xd0
	s_mov_b64 s[44:45], 0x1c800000
	s_mov_b64 s[46:47], 0x1ca00000
	s_mov_b64 s[48:49], 0x8800000
	s_mov_b64 s[50:51], 0xa800000
	s_mov_b32 s78, 0x8000
	s_mov_b32 s79, 0x10000
	s_mov_b32 s80, 0xf149f2ca
	s_mov_b32 s81, 0xefa18f08
	s_mov_b64 s[52:53], 0x6800000
	v_mov_b32_e32 v147, 0xf149f2ca
	s_mov_b32 s82, 0
	s_branch .LBB0_408
.LBB0_407:
	ds_bpermute_b32 v0, v126, v152
	v_lshlrev_b32_e32 v69, 3, v148
	v_lshlrev_b32_e32 v70, 6, v131
	v_and_b32_e32 v69, 0xfffff000, v69
	v_mov_b32_e32 v2, s3
	s_waitcnt lgkmcnt(0)
	v_add_f32_e32 v0, v152, v0
	ds_bpermute_b32 v68, v127, v0
	ds_read_b64 v[2:3], v2
	v_mov_b32_e32 v131, v1
	s_add_i32 s82, s82, 1
	s_cmp_eq_u32 s82, 4
	s_waitcnt lgkmcnt(1)
	v_add_f32_e32 v0, v0, v68
	v_div_scale_f32 v71, s[34:35], v0, v0, 1.0
	v_rcp_f32_e32 v72, v71
	v_or3_b32 v68, v69, v70, v163
	v_div_scale_f32 v69, vcc, 1.0, v0, 1.0
	v_fma_f32 v70, -v71, v72, 1.0
	v_fmac_f32_e32 v72, v70, v72
	v_mul_f32_e32 v70, v69, v72
	v_fma_f32 v73, -v71, v70, v69
	v_fmac_f32_e32 v70, v73, v72
	v_fma_f32 v69, -v71, v70, v69
	v_div_fmas_f32 v69, v69, v72, v70
	v_div_fixup_f32 v70, v69, v0, 1.0
	v_ashrrev_i32_e32 v69, 31, v68
	v_lshlrev_b64 v[68:69], 10, v[68:69]
	s_waitcnt lgkmcnt(0)
	v_lshl_add_u64 v[2:3], v[2:3], 0, v[68:69]
	v_lshlrev_b32_e32 v0, 1, v104
	v_lshl_add_u64 v[2:3], v[2:3], 0, v[0:1]
	v_lshl_add_u64 v[2:3], v[2:3], 0, v[130:131]
	v_lshl_add_u64 v[68:69], v[2:3], 0, s[52:53]
	v_pk_mul_f32 v[64:65], v[64:65], v[70:71] op_sel_hi:[1,0]
	v_pk_mul_f32 v[66:67], v[66:67], v[70:71] op_sel_hi:[1,0]
	v_add_co_u32_e32 v2, vcc, s74, v2
	v_cvt_pk_bf16_f32 v64, v64, v65
	v_cvt_pk_bf16_f32 v65, v66, v67
	v_addc_co_u32_e32 v3, vcc, 0, v3, vcc
	global_store_dwordx2 v[2:3], v[64:65], off
	v_pk_mul_f32 v[2:3], v[60:61], v[70:71] op_sel_hi:[1,0]
	v_pk_mul_f32 v[60:61], v[62:63], v[70:71] op_sel_hi:[1,0]
	v_cvt_pk_bf16_f32 v2, v2, v3
	v_cvt_pk_bf16_f32 v3, v60, v61
	global_store_dwordx2 v[68:69], v[2:3], off offset:32
	v_pk_mul_f32 v[2:3], v[56:57], v[70:71] op_sel_hi:[1,0]
	v_pk_mul_f32 v[56:57], v[58:59], v[70:71] op_sel_hi:[1,0]
	v_cvt_pk_bf16_f32 v2, v2, v3
	v_cvt_pk_bf16_f32 v3, v56, v57
	global_store_dwordx2 v[68:69], v[2:3], off offset:64
	v_pk_mul_f32 v[2:3], v[52:53], v[70:71] op_sel_hi:[1,0]
	v_pk_mul_f32 v[52:53], v[54:55], v[70:71] op_sel_hi:[1,0]
	v_cvt_pk_bf16_f32 v2, v2, v3
	v_cvt_pk_bf16_f32 v3, v52, v53
	global_store_dwordx2 v[68:69], v[2:3], off offset:96
	s_cbranch_scc1 .LBB0_462
.LBB0_408:
	v_lshl_add_u32 v148, s82, 1, v101
	v_bfe_u32 v2, v148, 6, 3
	v_mul_u32_u24_e32 v53, 0x1d1, v2
	v_lshlrev_b32_e32 v104, 6, v2
	v_and_b32_e32 v2, 0xfffffe00, v148
	v_or3_b32 v2, v2, v135, v104
	v_add_u32_e32 v55, 2, v148
	v_ashrrev_i32_e32 v3, 31, v2
	v_and_b32_e32 v57, 63, v55
	v_lshlrev_b64 v[106:107], 9, v[2:3]
	v_lshlrev_b64 v[108:109], 13, v[2:3]
	v_sub_u32_e64 v2, v57, 4 clamp
	v_min_u32_e32 v2, 56, v2
	v_lshlrev_b32_e32 v3, 3, v55
	v_lshlrev_b32_e32 v56, 6, v2
	v_and_or_b32 v58, v3, s72, v154
	v_or_b32_e32 v2, v58, v56
	v_ashrrev_i32_e32 v3, 31, v2
	v_and_b32_e32 v131, 63, v148
	v_lshlrev_b64 v[110:111], 10, v[2:3]
	v_and_or_b32 v2, v55, s73, v135
	v_sub_u32_e64 v0, v131, 4 clamp
	v_ashrrev_i32_e32 v3, 31, v2
	v_min_u32_e32 v0, 56, v0
	v_ashrrev_i32_e32 v52, 9, v148
	v_lshlrev_b64 v[112:113], 13, v[2:3]
	v_lshl_or_b32 v2, v57, 6, v58
	v_lshl_or_b32 v149, v52, 8, v154
	v_lshlrev_b32_e32 v54, 12, v52
	v_lshlrev_b32_e32 v52, 6, v0
	v_ashrrev_i32_e32 v3, 31, v2
	v_or3_b32 v150, v54, v154, v52
	v_and_b32_e32 v54, 0x1c0, v55
	v_lshlrev_b64 v[114:115], 10, v[2:3]
	v_sub_u32_e32 v0, v0, v131
	v_mov_b32_e32 v2, v1
	v_mov_b32_e32 v3, v1
	s_cmp_lt_u32 s82, 3
	v_add_u32_e32 v151, 7, v0
	v_add_lshl_u32 v116, v133, v53, 2
	v_mov_b32_e32 v0, v1
	v_lshlrev_b32_e32 v118, 1, v52
	v_lshlrev_b32_e32 v120, 1, v54
	v_lshlrev_b32_e32 v122, 1, v56
	v_mov_b64_e32 v[54:55], v[2:3]
	v_mov_b64_e32 v[58:59], v[2:3]
	v_mov_b64_e32 v[62:63], v[2:3]
	v_mov_b64_e32 v[66:67], v[2:3]
	s_cselect_b64 s[54:55], -1, 0
	v_mov_b32_e32 v117, v1
	v_mov_b64_e32 v[52:53], v[0:1]
	v_mov_b64_e32 v[56:57], v[0:1]
	v_mov_b64_e32 v[60:61], v[0:1]
	v_mov_b64_e32 v[64:65], v[0:1]
	v_mov_b32_e32 v152, v1
	v_mov_b32_e32 v153, 0xf149f2ca
	s_mov_b32 s83, s39
	s_branch .LBB0_410
